# GEMM accumulator zeroing with v_mov_b64 pairs (64 instead of 128 moves per tile)
# speedup vs baseline: 1.0082x; 1.0064x over previous
.LBB0_134:
	s_ashr_i32 s47, s46, 31
	s_lshl_b64 s[6:7], s[46:47], 19
	s_add_u32 s48, s92, s6
	s_addc_u32 s49, s93, s7
	s_and_b64 s[6:7], s[38:39], exec
	s_cselect_b32 s47, s49, s53
	s_cselect_b32 s68, s48, s52
	s_ashr_i32 s45, s44, 31
	s_lshl_b64 s[6:7], s[44:45], 19
	s_add_u32 s50, s58, s6
	s_addc_u32 s51, s59, s7
	s_and_b64 s[6:7], s[38:39], exec
	s_cselect_b32 s45, s51, s55
	s_cselect_b32 s69, s50, s54
	s_add_u32 s52, s52, 0x40080
	s_addc_u32 s53, s53, 0
	s_add_u32 s70, s54, 0x100
	v_mov_b32_e32 v2, 0
	s_addc_u32 s71, s55, 0
	s_mov_b32 s72, -2
	v_mov_b32_e32 v3, v2
	v_mov_b64_e32 v[4:5], 0
	v_mov_b64_e32 v[6:7], 0
	v_mov_b64_e32 v[8:9], 0
	v_mov_b64_e32 v[18:19], 0
	v_mov_b64_e32 v[20:21], 0
	v_mov_b64_e32 v[22:23], 0
	v_mov_b64_e32 v[24:25], 0
	s_waitcnt vmcnt(0)
	v_mov_b64_e32 v[34:35], 0
	v_mov_b64_e32 v[36:37], 0
	v_mov_b64_e32 v[38:39], 0
	v_mov_b64_e32 v[40:41], 0
	v_mov_b64_e32 v[50:51], 0
	v_mov_b64_e32 v[52:53], 0
	v_mov_b64_e32 v[54:55], 0
	v_mov_b64_e32 v[56:57], 0
	v_mov_b64_e32 v[10:11], 0
	v_mov_b64_e32 v[12:13], 0
	v_mov_b64_e32 v[14:15], 0
	v_mov_b64_e32 v[16:17], 0
	v_mov_b64_e32 v[26:27], 0
	v_mov_b64_e32 v[28:29], 0
	v_mov_b64_e32 v[30:31], 0
	v_mov_b64_e32 v[32:33], 0
	v_mov_b64_e32 v[42:43], 0
	v_mov_b64_e32 v[44:45], 0
	v_mov_b64_e32 v[46:47], 0
	v_mov_b64_e32 v[48:49], 0
	v_mov_b64_e32 v[58:59], 0
	v_mov_b64_e32 v[60:61], 0
	v_mov_b64_e32 v[62:63], 0
	v_mov_b64_e32 v[64:65], 0
	v_mov_b64_e32 v[66:67], 0
	v_mov_b64_e32 v[68:69], 0
	v_mov_b64_e32 v[70:71], 0
	v_mov_b64_e32 v[72:73], 0
	v_mov_b64_e32 v[82:83], 0
	v_mov_b64_e32 v[84:85], 0
	v_mov_b64_e32 v[86:87], 0
	v_mov_b64_e32 v[88:89], 0
	v_mov_b64_e32 v[98:99], 0
	v_mov_b64_e32 v[100:101], 0
	v_mov_b64_e32 v[102:103], 0
	v_mov_b64_e32 v[104:105], 0
	v_mov_b64_e32 v[114:115], 0
	v_mov_b64_e32 v[116:117], 0
	v_mov_b64_e32 v[118:119], 0
	v_mov_b64_e32 v[120:121], 0
	v_mov_b64_e32 v[74:75], 0
	v_mov_b64_e32 v[76:77], 0
	v_mov_b64_e32 v[78:79], 0
	v_mov_b64_e32 v[80:81], 0
	v_mov_b64_e32 v[90:91], 0
	v_mov_b64_e32 v[92:93], 0
	v_mov_b64_e32 v[94:95], 0
	v_mov_b64_e32 v[96:97], 0
	v_mov_b64_e32 v[106:107], 0
	v_mov_b64_e32 v[108:109], 0
	v_mov_b64_e32 v[110:111], 0
	v_mov_b64_e32 v[112:113], 0
	v_mov_b64_e32 v[122:123], 0
	v_mov_b64_e32 v[124:125], 0
	v_mov_b64_e32 v[126:127], 0
	v_mov_b64_e32 v[128:129], 0

.LBB0_230:
	s_ashr_i32 s53, s52, 31
	s_lshl_b64 s[24:25], s[52:53], 19
	s_add_u32 s54, s92, s24
	s_addc_u32 s55, s93, s25
	s_and_b64 s[24:25], s[38:39], exec
	s_cselect_b32 s37, s55, s1
	s_cselect_b32 s53, s54, s0
	s_ashr_i32 s51, s50, 31
	s_lshl_b64 s[24:25], s[50:51], 19
	s_add_u32 s56, s60, s24
	s_addc_u32 s57, s61, s25
	s_and_b64 s[24:25], s[38:39], exec
	s_cselect_b32 s51, s57, s41
	s_cselect_b32 s58, s56, s40
	s_add_u32 s0, s0, 0x40080
	s_addc_u32 s1, s1, 0
	s_add_u32 s59, s40, 0x100
	v_mov_b32_e32 v2, 0
	s_addc_u32 s70, s41, 0
	s_mov_b32 s71, -2
	v_mov_b32_e32 v3, v2
	v_mov_b64_e32 v[4:5], 0
	v_mov_b64_e32 v[6:7], 0
	v_mov_b64_e32 v[8:9], 0
	v_mov_b64_e32 v[34:35], 0
	v_mov_b64_e32 v[36:37], 0
	v_mov_b64_e32 v[38:39], 0
	v_mov_b64_e32 v[40:41], 0
	v_mov_b64_e32 v[50:51], 0
	v_mov_b64_e32 v[52:53], 0
	v_mov_b64_e32 v[54:55], 0
	v_mov_b64_e32 v[56:57], 0
	v_mov_b64_e32 v[66:67], 0
	v_mov_b64_e32 v[68:69], 0
	v_mov_b64_e32 v[70:71], 0
	v_mov_b64_e32 v[72:73], 0
	v_mov_b64_e32 v[18:19], 0
	v_mov_b64_e32 v[20:21], 0
	v_mov_b64_e32 v[22:23], 0
	v_mov_b64_e32 v[24:25], 0
	v_mov_b64_e32 v[42:43], 0
	v_mov_b64_e32 v[44:45], 0
	v_mov_b64_e32 v[46:47], 0
	v_mov_b64_e32 v[48:49], 0
	v_mov_b64_e32 v[58:59], 0
	v_mov_b64_e32 v[60:61], 0
	v_mov_b64_e32 v[62:63], 0
	v_mov_b64_e32 v[64:65], 0
	v_mov_b64_e32 v[74:75], 0
	v_mov_b64_e32 v[76:77], 0
	v_mov_b64_e32 v[78:79], 0
	v_mov_b64_e32 v[80:81], 0
	v_mov_b64_e32 v[82:83], 0
	v_mov_b64_e32 v[84:85], 0
	v_mov_b64_e32 v[86:87], 0
	v_mov_b64_e32 v[88:89], 0
	v_mov_b64_e32 v[98:99], 0
	v_mov_b64_e32 v[100:101], 0
	v_mov_b64_e32 v[102:103], 0
	v_mov_b64_e32 v[104:105], 0
	v_mov_b64_e32 v[114:115], 0
	v_mov_b64_e32 v[116:117], 0
	v_mov_b64_e32 v[118:119], 0
	v_mov_b64_e32 v[120:121], 0
	v_mov_b64_e32 v[130:131], 0
	v_mov_b64_e32 v[132:133], 0
	v_mov_b64_e32 v[134:135], 0
	v_mov_b64_e32 v[136:137], 0
	v_mov_b64_e32 v[90:91], 0
	v_mov_b64_e32 v[92:93], 0
	v_mov_b64_e32 v[94:95], 0
	v_mov_b64_e32 v[96:97], 0
	v_mov_b64_e32 v[106:107], 0
	v_mov_b64_e32 v[108:109], 0
	v_mov_b64_e32 v[110:111], 0
	v_mov_b64_e32 v[112:113], 0
	v_mov_b64_e32 v[122:123], 0
	v_mov_b64_e32 v[124:125], 0
	v_mov_b64_e32 v[126:127], 0
	v_mov_b64_e32 v[128:129], 0
	v_mov_b64_e32 v[138:139], 0
	v_mov_b64_e32 v[140:141], 0
	v_mov_b64_e32 v[142:143], 0
	v_mov_b64_e32 v[144:145], 0

.LBB0_559:
	s_ashr_i32 s47, s46, 31
	s_lshl_b64 s[24:25], s[46:47], 19
	s_add_u32 s48, s92, s24
	s_addc_u32 s49, s93, s25
	s_and_b64 s[24:25], s[38:39], exec
	s_cselect_b32 s47, s49, s41
	s_cselect_b32 s62, s48, s40
	s_ashr_i32 s45, s44, 31
	s_lshl_b64 s[24:25], s[44:45], 19
	s_add_u32 s50, s8, s24
	s_addc_u32 s51, s35, s25
	s_and_b64 s[24:25], s[38:39], exec
	s_cselect_b32 s45, s51, s43
	s_cselect_b32 s63, s50, s42
	s_add_u32 s40, s40, 0x40080
	s_addc_u32 s41, s41, 0
	s_add_u32 s64, s42, 0x100
	v_mov_b32_e32 v2, 0
	s_addc_u32 s65, s43, 0
	s_mov_b32 s66, -2
	v_mov_b32_e32 v3, v2
	v_mov_b64_e32 v[4:5], 0
	v_mov_b64_e32 v[6:7], 0
	v_mov_b64_e32 v[8:9], 0
	v_mov_b64_e32 v[18:19], 0
	v_mov_b64_e32 v[20:21], 0
	v_mov_b64_e32 v[22:23], 0
	v_mov_b64_e32 v[24:25], 0
	v_mov_b64_e32 v[34:35], 0
	v_mov_b64_e32 v[36:37], 0
	v_mov_b64_e32 v[38:39], 0
	v_mov_b64_e32 v[40:41], 0
	v_mov_b64_e32 v[50:51], 0
	v_mov_b64_e32 v[52:53], 0
	v_mov_b64_e32 v[54:55], 0
	v_mov_b64_e32 v[56:57], 0
	v_mov_b64_e32 v[10:11], 0
	v_mov_b64_e32 v[12:13], 0
	v_mov_b64_e32 v[14:15], 0
	v_mov_b64_e32 v[16:17], 0
	v_mov_b64_e32 v[26:27], 0
	v_mov_b64_e32 v[28:29], 0
	v_mov_b64_e32 v[30:31], 0
	v_mov_b64_e32 v[32:33], 0
	v_mov_b64_e32 v[42:43], 0
	v_mov_b64_e32 v[44:45], 0
	v_mov_b64_e32 v[46:47], 0
	v_mov_b64_e32 v[48:49], 0
	v_mov_b64_e32 v[58:59], 0
	v_mov_b64_e32 v[60:61], 0
	v_mov_b64_e32 v[62:63], 0
	v_mov_b64_e32 v[64:65], 0
	v_mov_b64_e32 v[66:67], 0
	v_mov_b64_e32 v[68:69], 0
	v_mov_b64_e32 v[70:71], 0
	v_mov_b64_e32 v[72:73], 0
	v_mov_b64_e32 v[90:91], 0
	v_mov_b64_e32 v[92:93], 0
	v_mov_b64_e32 v[94:95], 0
	v_mov_b64_e32 v[96:97], 0
	v_mov_b64_e32 v[114:115], 0
	v_mov_b64_e32 v[116:117], 0
	v_mov_b64_e32 v[122:123], 0
	v_mov_b64_e32 v[124:125], 0
	v_mov_b64_e32 v[146:147], 0
	v_mov_b64_e32 v[148:149], 0
	v_mov_b64_e32 v[150:151], 0
	v_mov_b64_e32 v[152:153], 0
	v_mov_b64_e32 v[78:79], 0
	v_mov_b64_e32 v[80:81], 0
	v_mov_b64_e32 v[82:83], 0
	v_mov_b64_e32 v[84:85], 0
	v_mov_b64_e32 v[106:107], 0
	v_mov_b64_e32 v[108:109], 0
	v_mov_b64_e32 v[110:111], 0
	v_mov_b64_e32 v[112:113], 0
	v_mov_b64_e32 v[130:131], 0
	v_mov_b64_e32 v[132:133], 0
	v_mov_b64_e32 v[134:135], 0
	v_mov_b64_e32 v[136:137], 0
	v_mov_b64_e32 v[158:159], 0
	v_mov_b64_e32 v[160:161], 0
	v_mov_b64_e32 v[166:167], 0
	v_mov_b64_e32 v[168:169], 0

.LBB0_762:
	s_add_u32 s50, s50, 0x80
	s_addc_u32 s51, s51, 0
	s_add_u32 s37, s52, 0x100
	v_mov_b32_e32 v2, 0
	s_addc_u32 s54, s53, 0
	s_mov_b32 s24, 0
	v_mov_b32_e32 v3, v2
	v_mov_b64_e32 v[4:5], 0
	s_waitcnt lgkmcnt(0)
	v_mov_b64_e32 v[6:7], 0
	v_mov_b64_e32 v[8:9], 0
	v_mov_b64_e32 v[18:19], 0
	v_mov_b64_e32 v[20:21], 0
	v_mov_b64_e32 v[22:23], 0
	v_mov_b64_e32 v[24:25], 0
	s_waitcnt vmcnt(0)
	v_mov_b64_e32 v[34:35], 0
	v_mov_b64_e32 v[36:37], 0
	v_mov_b64_e32 v[38:39], 0
	v_mov_b64_e32 v[40:41], 0
	v_mov_b64_e32 v[50:51], 0
	v_mov_b64_e32 v[52:53], 0
	v_mov_b64_e32 v[54:55], 0
	v_mov_b64_e32 v[56:57], 0
	v_mov_b64_e32 v[10:11], 0
	v_mov_b64_e32 v[12:13], 0
	v_mov_b64_e32 v[14:15], 0
	v_mov_b64_e32 v[16:17], 0
	v_mov_b64_e32 v[26:27], 0
	v_mov_b64_e32 v[28:29], 0
	v_mov_b64_e32 v[30:31], 0
	v_mov_b64_e32 v[32:33], 0
	v_mov_b64_e32 v[42:43], 0
	v_mov_b64_e32 v[44:45], 0
	v_mov_b64_e32 v[46:47], 0
	v_mov_b64_e32 v[48:49], 0
	v_mov_b64_e32 v[58:59], 0
	v_mov_b64_e32 v[60:61], 0
	v_mov_b64_e32 v[62:63], 0
	v_mov_b64_e32 v[64:65], 0
	v_mov_b64_e32 v[66:67], 0
	v_mov_b64_e32 v[68:69], 0
	v_mov_b64_e32 v[70:71], 0
	v_mov_b64_e32 v[72:73], 0
	v_mov_b64_e32 v[82:83], 0
	v_mov_b64_e32 v[84:85], 0
	v_mov_b64_e32 v[86:87], 0
	v_mov_b64_e32 v[88:89], 0
	v_mov_b64_e32 v[98:99], 0
	v_mov_b64_e32 v[100:101], 0
	v_mov_b64_e32 v[102:103], 0
	v_mov_b64_e32 v[104:105], 0
	v_mov_b64_e32 v[114:115], 0
	v_mov_b64_e32 v[116:117], 0
	v_mov_b64_e32 v[118:119], 0
	v_mov_b64_e32 v[120:121], 0
	v_mov_b64_e32 v[74:75], 0
	v_mov_b64_e32 v[76:77], 0
	v_mov_b64_e32 v[78:79], 0
	v_mov_b64_e32 v[80:81], 0
	v_mov_b64_e32 v[90:91], 0
	v_mov_b64_e32 v[92:93], 0
	v_mov_b64_e32 v[94:95], 0
	v_mov_b64_e32 v[96:97], 0
	v_mov_b64_e32 v[106:107], 0
	v_mov_b64_e32 v[108:109], 0
	v_mov_b64_e32 v[110:111], 0
	v_mov_b64_e32 v[112:113], 0
	v_mov_b64_e32 v[126:127], 0
	v_mov_b64_e32 v[128:129], 0
	v_mov_b64_e32 v[130:131], 0
	v_mov_b64_e32 v[132:133], 0
